# stack1 plus SGPR-base (saddr) LDS-DMA loads in the gate/up K-loop: 16 VALU 64-bit address adds per iteration replaced by SALU, 32-bit VGPR offsets
# baseline (speedup 1.0000x reference)
; #define PG8_STAGE(bufoff, gbase, voff) do { _Pragma("unroll") for (int _i = 0; _i < 2; ++_i) \
;         __builtin_amdgcn_global_load_lds((const unsigned*)((const char*)(gbase) + (voff)[_i]), (LAS unsigned*)(lds + (bufoff) + ldsw + _i * 8192), 16, 0, 0); } while (0)
; #define PG8_LDA(dst, b, h) do { _Pragma("unroll") for (int m = 0; m < 4; ++m) _Pragma("unroll") for (int k = 0; k < 2; ++k) dst[m][k] = *(const LAS bf16x8*)(lds + PG8_SA(b, h) + aoff + m * 2048 + k * 1024); } while (0)
; #define PG8_LDB(dst, b, h) do { _Pragma("unroll") for (int n = 0; n < 2; ++n) _Pragma("unroll") for (int k = 0; k < 2; ++k) dst[n][k] = *(const LAS bf16x8*)(lds + PG8_SB(b, h) + boff + n * 2048 + k * 1024); } while (0)
; #define PG8_MMA(ai, bj, At, Bt) do { __builtin_amdgcn_s_setprio(1); _Pragma("unroll") for (int m = 0; m < 4; ++m) _Pragma("unroll") for (int n = 0; n < 2; ++n) _Pragma("unroll") for (int k = 0; k < 2; ++k) \
;         acc[ai][bj][m][n] = __builtin_amdgcn_mfma_f32_16x16x32_bf16(Bt[n][k], At[m][k], acc[ai][bj][m][n], 0, 0, 0); __builtin_amdgcn_s_setprio(0); } while (0)
; #define PG8_WAIT_V(n) asm volatile("s_waitcnt vmcnt(" #n ")" ::: "memory")
; #define PG8_WAIT_L(n) asm volatile("s_waitcnt lgkmcnt(" #n ")" ::: "memory")
; #define PG8_BAR __builtin_amdgcn_s_barrier()
; #define PG8_SCHED __builtin_amdgcn_sched_barrier(0)
; template <class Epi>
; DI void gemm_phase(LAS unsigned char* lds, const Gemm g, const StaticOrder& S, const Epi& E) {
;     ...
;             PG8_LDB(B0, 0, 0); PG8_LDB(B1, 0, 1); PG8_SCHED; PG8_LDA(At, 0, 0); PG8_STAGE(PG8_SA(1, 1), a1 + hstepA, voffA);
;             PG8_WAIT_V(8); PG8_WAIT_L(0); PG8_BAR; PG8_MMA(0, 0, At, B0); PG8_MMA(0, 1, At, B1); PG8_BAR; PG8_SCHED;
;             PG8_LDA(At, 0, 1); PG8_STAGE(PG8_SB(0, 0), b2, voffB); PG8_STAGE(PG8_SB(0, 1), b2 + hstepB, voffB); PG8_STAGE(PG8_SA(0, 0), a2, voffA);
;             PG8_WAIT_V(8); PG8_WAIT_L(0); PG8_BAR; PG8_MMA(1, 0, At, B0); PG8_MMA(1, 1, At, B1); PG8_BAR; PG8_SCHED;
.LBB0_705:
	ds_read_b128 v[150:153], v147
	ds_read_b128 v[154:157], v147 offset:1024
	ds_read_b128 v[158:161], v147 offset:2048
	ds_read_b128 v[162:165], v147 offset:3072
	ds_read_b128 v[166:169], v148
	ds_read_b128 v[170:173], v148 offset:1024
	ds_read_b128 v[174:177], v148 offset:2048
	ds_read_b128 v[182:185], v148 offset:3072
	s_add_i32 s63, s28, 2
	s_add_u32 s29, s26, 0xfff00080
	s_addc_u32 s30, s27, -1
	s_cmp_eq_u32 s54, s28
	s_cselect_b32 s28, s60, s61
	s_cselect_b32 s31, s17, s30
	s_cselect_b32 s30, s19, s29
	s_cselect_b32 s29, s59, s62
	s_add_i32 m0, s25, 0xc000
	ds_read_b128 v[186:189], v149
	ds_read_b128 v[190:193], v149 offset:1024
	ds_read_b128 v[194:197], v149 offset:2048
	ds_read_b128 v[198:201], v149 offset:3072
	ds_read_b128 v[202:205], v149 offset:4096
	ds_read_b128 v[206:209], v149 offset:5120
	ds_read_b128 v[210:213], v149 offset:6144
	ds_read_b128 v[214:217], v149 offset:7168
	global_load_lds_dwordx4 v136, s[26:27]
	s_add_i32 m0, s25, 0xe000
	s_nop 0
	global_load_lds_dwordx4 v138, s[26:27]
	s_waitcnt vmcnt(8)
	s_waitcnt lgkmcnt(0)
	s_setprio 1
	s_barrier
	v_mfma_f32_16x16x32_bf16 v[124:127], v[150:153], v[186:189], v[124:127]
	v_mfma_f32_16x16x32_bf16 v[124:127], v[154:157], v[190:193], v[124:127]
	v_mfma_f32_16x16x32_bf16 v[116:119], v[158:161], v[186:189], v[116:119]
	v_mfma_f32_16x16x32_bf16 v[116:119], v[162:165], v[190:193], v[116:119]
	v_mfma_f32_16x16x32_bf16 v[108:111], v[150:153], v[194:197], v[108:111]
	v_mfma_f32_16x16x32_bf16 v[108:111], v[154:157], v[198:201], v[108:111]
	v_mfma_f32_16x16x32_bf16 v[100:103], v[158:161], v[194:197], v[100:103]
	v_mfma_f32_16x16x32_bf16 v[100:103], v[162:165], v[198:201], v[100:103]
	v_mfma_f32_16x16x32_bf16 v[92:95], v[150:153], v[202:205], v[92:95]
	v_mfma_f32_16x16x32_bf16 v[92:95], v[154:157], v[206:209], v[92:95]
	v_mfma_f32_16x16x32_bf16 v[84:87], v[158:161], v[202:205], v[84:87]
	v_mfma_f32_16x16x32_bf16 v[84:87], v[162:165], v[206:209], v[84:87]
	v_mfma_f32_16x16x32_bf16 v[76:79], v[150:153], v[210:213], v[76:79]
	v_mfma_f32_16x16x32_bf16 v[76:79], v[154:157], v[214:217], v[76:79]
	v_mfma_f32_16x16x32_bf16 v[68:71], v[158:161], v[210:213], v[68:71]
	v_mfma_f32_16x16x32_bf16 v[68:71], v[162:165], v[214:217], v[68:71]
	s_setprio 0
	s_setprio 1
	v_mfma_f32_16x16x32_bf16 v[120:123], v[166:169], v[186:189], v[120:123]
	v_mfma_f32_16x16x32_bf16 v[120:123], v[170:173], v[190:193], v[120:123]
	v_mfma_f32_16x16x32_bf16 v[112:115], v[174:177], v[186:189], v[112:115]
	v_mfma_f32_16x16x32_bf16 v[112:115], v[182:185], v[190:193], v[112:115]
	v_mfma_f32_16x16x32_bf16 v[104:107], v[166:169], v[194:197], v[104:107]
	v_mfma_f32_16x16x32_bf16 v[104:107], v[170:173], v[198:201], v[104:107]
	v_mfma_f32_16x16x32_bf16 v[96:99], v[174:177], v[194:197], v[96:99]
	v_mfma_f32_16x16x32_bf16 v[96:99], v[182:185], v[198:201], v[96:99]
	v_mfma_f32_16x16x32_bf16 v[88:91], v[166:169], v[202:205], v[88:91]
	v_mfma_f32_16x16x32_bf16 v[88:91], v[170:173], v[206:209], v[88:91]
	v_mfma_f32_16x16x32_bf16 v[80:83], v[174:177], v[202:205], v[80:83]
	v_mfma_f32_16x16x32_bf16 v[80:83], v[182:185], v[206:209], v[80:83]
	v_mfma_f32_16x16x32_bf16 v[72:75], v[166:169], v[210:213], v[72:75]
	v_mfma_f32_16x16x32_bf16 v[72:75], v[170:173], v[214:217], v[72:75]
	v_mfma_f32_16x16x32_bf16 v[64:67], v[174:177], v[210:213], v[64:67]
	v_mfma_f32_16x16x32_bf16 v[64:67], v[182:185], v[214:217], v[64:67]
	s_setprio 0
	s_barrier
	s_add_i32 s64, s55, s39
	s_add_u32 s100, s30, 0x80
	s_addc_u32 s101, s31, 0
	s_mov_b32 m0, s64
	ds_read_b128 v[186:189], v149 offset:16384
	ds_read_b128 v[190:193], v149 offset:17408
	ds_read_b128 v[194:197], v149 offset:18432
	ds_read_b128 v[198:201], v149 offset:19456
	ds_read_b128 v[202:205], v149 offset:20480
	ds_read_b128 v[206:209], v149 offset:21504
	ds_read_b128 v[210:213], v149 offset:22528
	ds_read_b128 v[214:217], v149 offset:23552
	global_load_lds_dwordx4 v132, s[28:29]
	s_add_i32 m0, s64, 0x2000
	s_add_u32 s64, s28, 0x100000
	s_addc_u32 s65, s29, 0
	s_add_i32 s66, s56, s39
	global_load_lds_dwordx4 v128, s[28:29]
	s_mov_b32 m0, s66
	s_nop 0
	global_load_lds_dwordx4 v132, s[64:65]
	s_add_i32 m0, s66, 0x2000
	s_nop 0
	global_load_lds_dwordx4 v128, s[64:65]
	s_mov_b32 m0, s25
	s_nop 0
	global_load_lds_dwordx4 v134, s[30:31]
	s_mov_b32 m0, s42
	s_nop 0
	global_load_lds_dwordx4 v130, s[30:31]
	s_waitcnt vmcnt(8)
	s_waitcnt lgkmcnt(0)
	s_setprio 1
	s_barrier
	v_mfma_f32_16x16x32_bf16 v[60:63], v[150:153], v[186:189], v[60:63]
	v_mfma_f32_16x16x32_bf16 v[60:63], v[154:157], v[190:193], v[60:63]
	v_mfma_f32_16x16x32_bf16 v[52:55], v[158:161], v[186:189], v[52:55]
	v_mfma_f32_16x16x32_bf16 v[52:55], v[162:165], v[190:193], v[52:55]
	v_mfma_f32_16x16x32_bf16 v[44:47], v[150:153], v[194:197], v[44:47]
	v_mfma_f32_16x16x32_bf16 v[44:47], v[154:157], v[198:201], v[44:47]
	v_mfma_f32_16x16x32_bf16 v[36:39], v[158:161], v[194:197], v[36:39]
	v_mfma_f32_16x16x32_bf16 v[36:39], v[162:165], v[198:201], v[36:39]
	v_mfma_f32_16x16x32_bf16 v[28:31], v[150:153], v[202:205], v[28:31]
	v_mfma_f32_16x16x32_bf16 v[28:31], v[154:157], v[206:209], v[28:31]
	v_mfma_f32_16x16x32_bf16 v[20:23], v[158:161], v[202:205], v[20:23]
	v_mfma_f32_16x16x32_bf16 v[20:23], v[162:165], v[206:209], v[20:23]
	v_mfma_f32_16x16x32_bf16 v[12:15], v[150:153], v[210:213], v[12:15]
	v_mfma_f32_16x16x32_bf16 v[12:15], v[154:157], v[214:217], v[12:15]
	v_mfma_f32_16x16x32_bf16 v[4:7], v[158:161], v[210:213], v[4:7]
	v_mfma_f32_16x16x32_bf16 v[4:7], v[162:165], v[214:217], v[4:7]
	s_setprio 0
	s_setprio 1
	v_mfma_f32_16x16x32_bf16 v[56:59], v[166:169], v[186:189], v[56:59]
	v_mfma_f32_16x16x32_bf16 v[56:59], v[170:173], v[190:193], v[56:59]
	v_mfma_f32_16x16x32_bf16 v[48:51], v[174:177], v[186:189], v[48:51]
	v_mfma_f32_16x16x32_bf16 v[48:51], v[182:185], v[190:193], v[48:51]
	v_mfma_f32_16x16x32_bf16 v[40:43], v[166:169], v[194:197], v[40:43]
	v_mfma_f32_16x16x32_bf16 v[40:43], v[170:173], v[198:201], v[40:43]
	v_mfma_f32_16x16x32_bf16 v[32:35], v[174:177], v[194:197], v[32:35]
	v_mfma_f32_16x16x32_bf16 v[32:35], v[182:185], v[198:201], v[32:35]
	v_mfma_f32_16x16x32_bf16 v[24:27], v[166:169], v[202:205], v[24:27]
	v_mfma_f32_16x16x32_bf16 v[24:27], v[170:173], v[206:209], v[24:27]
	v_mfma_f32_16x16x32_bf16 v[16:19], v[174:177], v[202:205], v[16:19]
	v_mfma_f32_16x16x32_bf16 v[16:19], v[182:185], v[206:209], v[16:19]
	v_mfma_f32_16x16x32_bf16 v[8:11], v[166:169], v[210:213], v[8:11]
	v_mfma_f32_16x16x32_bf16 v[8:11], v[170:173], v[214:217], v[8:11]
	v_mfma_f32_16x16x32_bf16 v[0:3], v[174:177], v[210:213], v[0:3]
	v_mfma_f32_16x16x32_bf16 v[0:3], v[182:185], v[214:217], v[0:3]
	s_setprio 0
	s_barrier
; #define PG8_STAGE(bufoff, gbase, voff) do { _Pragma("unroll") for (int _i = 0; _i < 2; ++_i) \
;         __builtin_amdgcn_global_load_lds((const unsigned*)((const char*)(gbase) + (voff)[_i]), (LAS unsigned*)(lds + (bufoff) + ldsw + _i * 8192), 16, 0, 0); } while (0)
; #define PG8_LDA(dst, b, h) do { _Pragma("unroll") for (int m = 0; m < 4; ++m) _Pragma("unroll") for (int k = 0; k < 2; ++k) dst[m][k] = *(const LAS bf16x8*)(lds + PG8_SA(b, h) + aoff + m * 2048 + k * 1024); } while (0)
; #define PG8_LDB(dst, b, h) do { _Pragma("unroll") for (int n = 0; n < 2; ++n) _Pragma("unroll") for (int k = 0; k < 2; ++k) dst[n][k] = *(const LAS bf16x8*)(lds + PG8_SB(b, h) + boff + n * 2048 + k * 1024); } while (0)
; #define PG8_MMA(ai, bj, At, Bt) do { __builtin_amdgcn_s_setprio(1); _Pragma("unroll") for (int m = 0; m < 4; ++m) _Pragma("unroll") for (int n = 0; n < 2; ++n) _Pragma("unroll") for (int k = 0; k < 2; ++k) \
;         acc[ai][bj][m][n] = __builtin_amdgcn_mfma_f32_16x16x32_bf16(Bt[n][k], At[m][k], acc[ai][bj][m][n], 0, 0, 0); __builtin_amdgcn_s_setprio(0); } while (0)
; #define PG8_WAIT_V(n) asm volatile("s_waitcnt vmcnt(" #n ")" ::: "memory")
; #define PG8_WAIT_L(n) asm volatile("s_waitcnt lgkmcnt(" #n ")" ::: "memory")
; #define PG8_BAR __builtin_amdgcn_s_barrier()
; #define PG8_SCHED __builtin_amdgcn_sched_barrier(0)
; template <class Epi>
; DI void gemm_phase(LAS unsigned char* lds, const Gemm g, const StaticOrder& S, const Epi& E) {
;     ...
;             PG8_LDB(B0, 1, 0); PG8_LDB(B1, 1, 1); PG8_SCHED; PG8_LDA(At, 1, 0); PG8_STAGE(PG8_SA(0, 1), a2 + hstepA, voffA);
;             PG8_WAIT_V(8); PG8_WAIT_L(0); PG8_BAR; PG8_MMA(0, 0, At, B0); PG8_MMA(0, 1, At, B1); PG8_BAR; PG8_SCHED;
;             PG8_LDA(At, 1, 1); PG8_STAGE(PG8_SB(1, 0), b3, voffB); PG8_STAGE(PG8_SB(1, 1), b3 + hstepB, voffB); PG8_STAGE(PG8_SA(1, 0), a3, voffA);
;             PG8_WAIT_V(8); PG8_WAIT_L(0); PG8_BAR; PG8_MMA(1, 0, At, B0); PG8_MMA(1, 1, At, B1); PG8_BAR; PG8_SCHED;
	s_add_i32 s64, 0, 0x18000
	s_add_i32 s65, 0, 0x1c000
	v_add_u32_e32 v162, s64, v145
	v_add_u32_e32 v181, s65, v145
	ds_read_b128 v[150:153], v162
	ds_read_b128 v[154:157], v162 offset:1024
	ds_read_b128 v[158:161], v162 offset:2048
	ds_read_b128 v[162:165], v162 offset:3072
	ds_read_b128 v[166:169], v181
	ds_read_b128 v[170:173], v181 offset:1024
	ds_read_b128 v[174:177], v181 offset:2048
	ds_read_b128 v[182:185], v181 offset:3072
	s_add_u32 s30, s30, 0x100000
	s_addc_u32 s31, s31, 0
	s_mov_b32 m0, s43
	ds_read_b128 v[186:189], v149 offset:32768
	ds_read_b128 v[190:193], v149 offset:33792
	ds_read_b128 v[194:197], v149 offset:34816
	ds_read_b128 v[198:201], v149 offset:35840
	ds_read_b128 v[202:205], v149 offset:36864
	ds_read_b128 v[206:209], v149 offset:37888
	ds_read_b128 v[210:213], v149 offset:38912
	ds_read_b128 v[214:217], v149 offset:39936
	global_load_lds_dwordx4 v134, s[30:31]
	s_mov_b32 m0, s46
	s_nop 0
	global_load_lds_dwordx4 v130, s[30:31]
	s_waitcnt vmcnt(8)
	s_waitcnt lgkmcnt(0)
	s_setprio 1
	s_barrier
	v_mfma_f32_16x16x32_bf16 v[124:127], v[150:153], v[186:189], v[124:127]
	v_mfma_f32_16x16x32_bf16 v[124:127], v[154:157], v[190:193], v[124:127]
	v_mfma_f32_16x16x32_bf16 v[116:119], v[158:161], v[186:189], v[116:119]
	v_mfma_f32_16x16x32_bf16 v[116:119], v[162:165], v[190:193], v[116:119]
	v_mfma_f32_16x16x32_bf16 v[108:111], v[150:153], v[194:197], v[108:111]
	v_mfma_f32_16x16x32_bf16 v[108:111], v[154:157], v[198:201], v[108:111]
	v_mfma_f32_16x16x32_bf16 v[100:103], v[158:161], v[194:197], v[100:103]
	v_mfma_f32_16x16x32_bf16 v[100:103], v[162:165], v[198:201], v[100:103]
	v_mfma_f32_16x16x32_bf16 v[92:95], v[150:153], v[202:205], v[92:95]
	v_mfma_f32_16x16x32_bf16 v[92:95], v[154:157], v[206:209], v[92:95]
	v_mfma_f32_16x16x32_bf16 v[84:87], v[158:161], v[202:205], v[84:87]
	v_mfma_f32_16x16x32_bf16 v[84:87], v[162:165], v[206:209], v[84:87]
	v_mfma_f32_16x16x32_bf16 v[76:79], v[150:153], v[210:213], v[76:79]
	v_mfma_f32_16x16x32_bf16 v[76:79], v[154:157], v[214:217], v[76:79]
	v_mfma_f32_16x16x32_bf16 v[68:71], v[158:161], v[210:213], v[68:71]
	v_mfma_f32_16x16x32_bf16 v[68:71], v[162:165], v[214:217], v[68:71]
	s_setprio 0
	s_setprio 1
	v_mfma_f32_16x16x32_bf16 v[120:123], v[166:169], v[186:189], v[120:123]
	v_mfma_f32_16x16x32_bf16 v[120:123], v[170:173], v[190:193], v[120:123]
	v_mfma_f32_16x16x32_bf16 v[112:115], v[174:177], v[186:189], v[112:115]
	v_mfma_f32_16x16x32_bf16 v[112:115], v[182:185], v[190:193], v[112:115]
	v_mfma_f32_16x16x32_bf16 v[104:107], v[166:169], v[194:197], v[104:107]
	v_mfma_f32_16x16x32_bf16 v[104:107], v[170:173], v[198:201], v[104:107]
	v_mfma_f32_16x16x32_bf16 v[96:99], v[174:177], v[194:197], v[96:99]
	v_mfma_f32_16x16x32_bf16 v[96:99], v[182:185], v[198:201], v[96:99]
	v_mfma_f32_16x16x32_bf16 v[88:91], v[166:169], v[202:205], v[88:91]
	v_mfma_f32_16x16x32_bf16 v[88:91], v[170:173], v[206:209], v[88:91]
	v_mfma_f32_16x16x32_bf16 v[80:83], v[174:177], v[202:205], v[80:83]
	v_mfma_f32_16x16x32_bf16 v[80:83], v[182:185], v[206:209], v[80:83]
	v_mfma_f32_16x16x32_bf16 v[72:75], v[166:169], v[210:213], v[72:75]
	v_mfma_f32_16x16x32_bf16 v[72:75], v[170:173], v[214:217], v[72:75]
	v_mfma_f32_16x16x32_bf16 v[64:67], v[174:177], v[210:213], v[64:67]
	v_mfma_f32_16x16x32_bf16 v[64:67], v[182:185], v[214:217], v[64:67]
	s_setprio 0
	s_barrier
	s_add_i32 s30, s64, s39
	s_add_u32 s98, s28, 0x80
	s_addc_u32 s99, s29, 0
	s_mov_b32 m0, s30
	ds_read_b128 v[186:189], v149 offset:49152
	ds_read_b128 v[190:193], v149 offset:50176
	ds_read_b128 v[194:197], v149 offset:51200
	ds_read_b128 v[198:201], v149 offset:52224
	ds_read_b128 v[202:205], v149 offset:53248
	ds_read_b128 v[206:209], v149 offset:54272
	ds_read_b128 v[210:213], v149 offset:55296
	ds_read_b128 v[214:217], v149 offset:56320
	global_load_lds_dwordx4 v132, s[98:99]
	s_add_i32 m0, s30, 0x2000
	s_add_u32 s28, s28, 0x100080
	s_addc_u32 s29, s29, 0
	s_add_i32 s30, s65, s39
	global_load_lds_dwordx4 v128, s[98:99]
	s_mov_b32 m0, s30
	s_nop 0
	global_load_lds_dwordx4 v132, s[28:29]
	s_add_i32 m0, s30, 0x2000
	s_nop 0
	global_load_lds_dwordx4 v128, s[28:29]
	s_mov_b32 m0, s52
	s_nop 0
	global_load_lds_dwordx4 v134, s[100:101]
	s_mov_b32 m0, s53
	s_nop 0
	global_load_lds_dwordx4 v130, s[100:101]
	s_waitcnt vmcnt(8)
	s_waitcnt lgkmcnt(0)
	s_setprio 1
	s_barrier
	v_mfma_f32_16x16x32_bf16 v[60:63], v[150:153], v[186:189], v[60:63]
	v_mfma_f32_16x16x32_bf16 v[60:63], v[154:157], v[190:193], v[60:63]
	v_mfma_f32_16x16x32_bf16 v[52:55], v[158:161], v[186:189], v[52:55]
	v_mfma_f32_16x16x32_bf16 v[52:55], v[162:165], v[190:193], v[52:55]
	v_mfma_f32_16x16x32_bf16 v[44:47], v[150:153], v[194:197], v[44:47]
	v_mfma_f32_16x16x32_bf16 v[44:47], v[154:157], v[198:201], v[44:47]
	v_mfma_f32_16x16x32_bf16 v[36:39], v[158:161], v[194:197], v[36:39]
	v_mfma_f32_16x16x32_bf16 v[36:39], v[162:165], v[198:201], v[36:39]
	v_mfma_f32_16x16x32_bf16 v[28:31], v[150:153], v[202:205], v[28:31]
	v_mfma_f32_16x16x32_bf16 v[28:31], v[154:157], v[206:209], v[28:31]
	v_mfma_f32_16x16x32_bf16 v[20:23], v[158:161], v[202:205], v[20:23]
	v_mfma_f32_16x16x32_bf16 v[20:23], v[162:165], v[206:209], v[20:23]
	v_mfma_f32_16x16x32_bf16 v[12:15], v[150:153], v[210:213], v[12:15]
	v_mfma_f32_16x16x32_bf16 v[12:15], v[154:157], v[214:217], v[12:15]
	v_mfma_f32_16x16x32_bf16 v[4:7], v[158:161], v[210:213], v[4:7]
	v_mfma_f32_16x16x32_bf16 v[4:7], v[162:165], v[214:217], v[4:7]
	s_setprio 0
	s_setprio 1
	v_mfma_f32_16x16x32_bf16 v[56:59], v[166:169], v[186:189], v[56:59]
	v_mfma_f32_16x16x32_bf16 v[56:59], v[170:173], v[190:193], v[56:59]
	v_mfma_f32_16x16x32_bf16 v[48:51], v[174:177], v[186:189], v[48:51]
	v_mfma_f32_16x16x32_bf16 v[48:51], v[182:185], v[190:193], v[48:51]
	v_mfma_f32_16x16x32_bf16 v[40:43], v[166:169], v[194:197], v[40:43]
	v_mfma_f32_16x16x32_bf16 v[40:43], v[170:173], v[198:201], v[40:43]
	v_mfma_f32_16x16x32_bf16 v[32:35], v[174:177], v[194:197], v[32:35]
	v_mfma_f32_16x16x32_bf16 v[32:35], v[182:185], v[198:201], v[32:35]
	v_mfma_f32_16x16x32_bf16 v[24:27], v[166:169], v[202:205], v[24:27]
	v_mfma_f32_16x16x32_bf16 v[24:27], v[170:173], v[206:209], v[24:27]
	v_mfma_f32_16x16x32_bf16 v[16:19], v[174:177], v[202:205], v[16:19]
	v_mfma_f32_16x16x32_bf16 v[16:19], v[182:185], v[206:209], v[16:19]
	v_mfma_f32_16x16x32_bf16 v[8:11], v[166:169], v[210:213], v[8:11]
	v_mfma_f32_16x16x32_bf16 v[8:11], v[170:173], v[214:217], v[8:11]
	v_mfma_f32_16x16x32_bf16 v[0:3], v[174:177], v[210:213], v[0:3]
	v_mfma_f32_16x16x32_bf16 v[0:3], v[182:185], v[214:217], v[0:3]
	s_setprio 0
	s_barrier
	s_add_u32 s26, s26, 0x100
	s_addc_u32 s27, s27, 0
	s_add_u32 s61, s61, 0x100
	s_addc_u32 s62, s62, 0
	s_cmp_ge_i32 s63, s51
	s_mov_b32 s28, s63
	s_cbranch_scc0 .LBB0_705

; __global__ void __launch_bounds__(512, 2) mk_fwd(Params prm) {
	.amdhsa_kernel _Z6mk_fwd6Params
		.amdhsa_group_segment_fixed_size 0
		.amdhsa_private_segment_fixed_size 0
		.amdhsa_kernarg_size 448
		.amdhsa_user_sgpr_count 2
		.amdhsa_user_sgpr_dispatch_ptr 0
		.amdhsa_user_sgpr_queue_ptr 0
		.amdhsa_user_sgpr_kernarg_segment_ptr 1
		.amdhsa_user_sgpr_dispatch_id 0
		.amdhsa_user_sgpr_kernarg_preload_length 0
		.amdhsa_user_sgpr_kernarg_preload_offset 0
		.amdhsa_user_sgpr_private_segment_size 0
		.amdhsa_uses_dynamic_stack 0
		.amdhsa_enable_private_segment 0
		.amdhsa_system_sgpr_workgroup_id_x 1
		.amdhsa_system_sgpr_workgroup_id_y 0
		.amdhsa_system_sgpr_workgroup_id_z 0
		.amdhsa_system_sgpr_workgroup_info 0
		.amdhsa_system_vgpr_workitem_id 2
		.amdhsa_next_free_vgpr 254
		.amdhsa_next_free_sgpr 102
		.amdhsa_accum_offset 256
		.amdhsa_reserve_vcc 1
		.amdhsa_float_round_mode_32 0
		.amdhsa_float_round_mode_16_64 0
		.amdhsa_float_denorm_mode_32 3
		.amdhsa_float_denorm_mode_16_64 3
		.amdhsa_dx10_clamp 1
		.amdhsa_ieee_mode 1
		.amdhsa_fp16_overflow 0
		.amdhsa_tg_split 0
		.amdhsa_exception_fp_ieee_invalid_op 0
		.amdhsa_exception_fp_denorm_src 0
		.amdhsa_exception_fp_ieee_div_zero 0
		.amdhsa_exception_fp_ieee_overflow 0
		.amdhsa_exception_fp_ieee_underflow 0
		.amdhsa_exception_fp_ieee_inexact 0
		.amdhsa_exception_int_div_zero 0
	.end_amdhsa_kernel

; __global__ void __launch_bounds__(512, 2) mk_fwd(Params prm) {
amdhsa.kernels:
  - .agpr_count:     0
    .args:
      - .offset:         0
        .size:           192
        .value_kind:     by_value
      - .offset:         192
        .size:           4
        .value_kind:     hidden_block_count_x
      - .offset:         196
        .size:           4
        .value_kind:     hidden_block_count_y
      - .offset:         200
        .size:           4
        .value_kind:     hidden_block_count_z
      - .offset:         204
        .size:           2
        .value_kind:     hidden_group_size_x
      - .offset:         206
        .size:           2
        .value_kind:     hidden_group_size_y
      - .offset:         208
        .size:           2
        .value_kind:     hidden_group_size_z
      - .offset:         210
        .size:           2
        .value_kind:     hidden_remainder_x
      - .offset:         212
        .size:           2
        .value_kind:     hidden_remainder_y
      - .offset:         214
        .size:           2
        .value_kind:     hidden_remainder_z
      - .offset:         232
        .size:           8
        .value_kind:     hidden_global_offset_x
      - .offset:         240
        .size:           8
        .value_kind:     hidden_global_offset_y
      - .offset:         248
        .size:           8
        .value_kind:     hidden_global_offset_z
      - .offset:         256
        .size:           2
        .value_kind:     hidden_grid_dims
      - .offset:         280
        .size:           8
        .value_kind:     hidden_multigrid_sync_arg
      - .offset:         312
        .size:           4
        .value_kind:     hidden_dynamic_lds_size
    .group_segment_fixed_size: 0
    .kernarg_segment_align: 8
    .kernarg_segment_size: 448
    .language:       OpenCL C
    .language_version:
      - 2
      - 0
    .max_flat_workgroup_size: 512
    .name:           _Z6mk_fwd6Params
    .private_segment_fixed_size: 0
    .sgpr_count:     108
    .sgpr_spill_count: 0
    .symbol:         _Z6mk_fwd6Params.kd
    .uniform_work_group_size: 1
    .uses_dynamic_stack: false
    .vgpr_count:     254
    .vgpr_spill_count: 0
    .wavefront_size: 64
